# static priority raise (s_setprio 1) for waves 4..7 during attention B, reset at the end of the phase
# baseline (speedup 1.0000x reference)
.LBB0_377:
	s_cmpk_gt_i32 s33, 0x3ff
	s_cbranch_scc1 .LBB0_403
	v_lshrrev_b32_e32 v0, 2, v215
	v_lshlrev_b32_e32 v0, 5, v0
	v_or_b32_e32 v2, v181, v183
	v_and_b32_e32 v107, 64, v0
	v_bitop3_b32 v109, v0, 64, v0 bitop3:0xc
	v_lshl_add_u32 v0, v215, 2, 0
	v_lshlrev_b32_e32 v106, 7, v2
	v_add3_u32 v242, v106, v175, v176
	v_add_u32_e32 v111, 0x18000, v0
	v_lshlrev_b32_e32 v0, 4, v182
	v_lshlrev_b32_e32 v2, 2, v178
	v_sub_u32_e32 v0, v0, v2
	s_lshl_b32 s4, s92, 7
	v_subrev_u32_e32 v0, s4, v0
	v_and_b32_e32 v1, 7, v215
	v_add_u32_e32 v112, 0xfc, v0
	s_add_u32 s14, s50, 0x8221000
	v_lshlrev_b32_e32 v0, 1, v172
	s_addc_u32 s15, s51, 0
	s_lshl_b32 s16, s33, 8
	s_lshl_b32 s17, s86, 8
	v_bitop3_b32 v0, v0, v1, 4 bitop3:0x6c
	s_add_u32 s19, s50, 0x8221400
	v_mov_b32_e32 v99, 0
	v_lshlrev_b32_e32 v115, 3, v0
	v_mbcnt_lo_u32_b32 v0, -1, 0
	v_add_u32_e32 v108, 0x23f, v181
	v_sub_u32_e32 v110, 0x23f, v215
	s_mov_b32 s5, 0
	s_movk_i32 s18, 0xc00
	v_mul_u32_u24_e32 v113, 0xc00, v172
	s_addc_u32 s20, s51, 0
	s_mov_b32 s21, 0xcb8727c1
	s_movk_i32 s22, 0x284
	s_movk_i32 s23, 0xff00
	v_mov_b32_e32 v114, 0x100
	s_movk_i32 s24, 0x80f
	v_mov_b32_e32 v133, v99
	v_mov_b32_e32 v135, v99
	s_movk_i32 s25, 0xa40
	s_mov_b64 s[6:7], 0x60000
	v_lshlrev_b32_e32 v100, 1, v181
	s_add_i32 s26, 0, 0x18000
	v_mbcnt_hi_u32_b32 v116, -1, v0
	s_mov_b32 s27, s33
	s_mov_b32 s28, s33
	s_cmp_lt_u32 s92, 4
	s_cbranch_scc1 .Lb_prio_skip
	s_setprio 1
.Lb_prio_skip:
	s_branch .LBB0_380
.LBB0_379:
	v_and_b32_e32 v33, 64, v116
	v_xor_b32_e32 v32, 32, v116
	v_add_u32_e32 v33, 64, v33
	v_cmp_lt_i32_e32 vcc, v32, v33
	s_lshl_b32 s12, s30, 6
	s_add_i32 s28, s28, s86
	v_cndmask_b32_e32 v32, v116, v32, vcc
	v_lshlrev_b32_e32 v32, 2, v32
	ds_bpermute_b32 v32, v32, v101
	s_add_i32 s16, s16, s17
	s_add_i32 s27, s27, s86
	s_waitcnt lgkmcnt(0)
	v_add_f32_e32 v32, v101, v32
	v_div_scale_f32 v33, s[30:31], v32, v32, 1.0
	v_rcp_f32_e32 v34, v33
	v_div_scale_f32 v35, vcc, 1.0, v32, 1.0
	v_mov_b32_e32 v101, v99
	v_fma_f32 v36, -v33, v34, 1.0
	v_fmac_f32_e32 v34, v36, v34
	v_mul_f32_e32 v36, v35, v34
	v_fma_f32 v37, -v33, v36, v35
	v_fmac_f32_e32 v36, v37, v34
	v_fma_f32 v33, -v33, v36, v35
	v_div_fmas_f32 v33, v33, v34, v36
	v_div_fixup_f32 v32, v33, v32, 1.0
	v_pk_mul_f32 v[16:17], v[16:17], v[32:33] op_sel_hi:[1,0]
	v_pk_mul_f32 v[18:19], v[18:19], v[32:33] op_sel_hi:[1,0]
	v_pk_mul_f32 v[20:21], v[20:21], v[32:33] op_sel_hi:[1,0]
	v_pk_mul_f32 v[22:23], v[22:23], v[32:33] op_sel_hi:[1,0]
	v_pk_mul_f32 v[24:25], v[24:25], v[32:33] op_sel_hi:[1,0]
	v_pk_mul_f32 v[26:27], v[26:27], v[32:33] op_sel_hi:[1,0]
	v_pk_mul_f32 v[28:29], v[28:29], v[32:33] op_sel_hi:[1,0]
	v_pk_mul_f32 v[30:31], v[30:31], v[32:33] op_sel_hi:[1,0]
	v_pk_mul_f32 v[0:1], v[0:1], v[32:33] op_sel_hi:[1,0]
	v_pk_mul_f32 v[2:3], v[2:3], v[32:33] op_sel_hi:[1,0]
	v_pk_mul_f32 v[4:5], v[4:5], v[32:33] op_sel_hi:[1,0]
	v_pk_mul_f32 v[6:7], v[6:7], v[32:33] op_sel_hi:[1,0]
	v_pk_mul_f32 v[8:9], v[8:9], v[32:33] op_sel_hi:[1,0]
	v_pk_mul_f32 v[10:11], v[10:11], v[32:33] op_sel_hi:[1,0]
	v_pk_mul_f32 v[12:13], v[12:13], v[32:33] op_sel_hi:[1,0]
	v_pk_mul_f32 v[14:15], v[14:15], v[32:33] op_sel_hi:[1,0]
	v_mov_b32_e32 v33, s29
	v_or_b32_e32 v32, s4, v178
	v_lshlrev_b64 v[32:33], 11, v[32:33]
	v_lshl_add_u64 v[32:33], s[90:91], 0, v[32:33]
	s_lshl_b32 s4, s12, 1
	v_lshl_add_u64 v[32:33], v[32:33], 0, s[4:5]
	v_lshl_add_u64 v[32:33], v[32:33], 0, v[100:101]
	v_cvt_pk_bf16_f32 v16, v16, v17
	v_cvt_pk_bf16_f32 v17, v18, v19
	v_cvt_pk_bf16_f32 v0, v0, v1
	v_cvt_pk_bf16_f32 v1, v2, v3
	global_store_dwordx2 v[32:33], v[16:17], off offset:1024
	v_cvt_pk_bf16_f32 v16, v20, v21
	v_cvt_pk_bf16_f32 v17, v22, v23
	global_store_dwordx2 v[32:33], v[0:1], off offset:1088
	v_cvt_pk_bf16_f32 v0, v4, v5
	v_cvt_pk_bf16_f32 v1, v6, v7
	global_store_dwordx2 v[32:33], v[16:17], off offset:1040
	v_cvt_pk_bf16_f32 v16, v24, v25
	v_cvt_pk_bf16_f32 v17, v26, v27
	global_store_dwordx2 v[32:33], v[0:1], off offset:1104
	v_cvt_pk_bf16_f32 v0, v8, v9
	v_cvt_pk_bf16_f32 v1, v10, v11
	global_store_dwordx2 v[32:33], v[16:17], off offset:1056
	v_cvt_pk_bf16_f32 v16, v28, v29
	v_cvt_pk_bf16_f32 v17, v30, v31
	global_store_dwordx2 v[32:33], v[0:1], off offset:1120
	v_cvt_pk_bf16_f32 v0, v12, v13
	v_cvt_pk_bf16_f32 v1, v14, v15
	s_cmpk_gt_i32 s28, 0x3ff
	global_store_dwordx2 v[32:33], v[16:17], off offset:1072
	global_store_dwordx2 v[32:33], v[0:1], off offset:1136
	s_cbranch_scc1 .LBB0_403

.LBB0_403:
	s_setprio 0
	s_cmp_gt_i32 s89, 3
	s_cselect_b64 s[4:5], -1, 0
	s_and_b64 s[2:3], s[2:3], s[4:5]
	v_readlane_b32 s64, v243, 0
	v_readlane_b32 s60, v243, 19
	s_andn2_b64 vcc, exec, s[2:3]
	v_readlane_b32 s65, v243, 1
	v_readlane_b32 s61, v243, 20
	v_readlane_b32 s66, v243, 2
	v_readlane_b32 s67, v243, 3
	v_readlane_b32 s68, v243, 4
	v_readlane_b32 s69, v243, 5
	v_readlane_b32 s70, v243, 6
	v_readlane_b32 s71, v243, 7
	v_readlane_b32 s72, v243, 8
	v_readlane_b32 s73, v243, 9
	v_readlane_b32 s74, v243, 10
	v_readlane_b32 s75, v243, 11
	v_readlane_b32 s76, v243, 12
	v_readlane_b32 s77, v243, 13
	v_readlane_b32 s78, v243, 14
	v_readlane_b32 s79, v243, 15
	s_cbranch_vccnz .LBB0_457
	s_waitcnt vmcnt(0)
	s_waitcnt vmcnt(0) lgkmcnt(0)
	s_barrier
	s_and_saveexec_b64 s[2:3], s[96:97]
	s_cbranch_execz .LBB0_456
	s_add_i32 s6, 0, 0x23fc0
	v_mov_b32_e32 v0, s6
	s_waitcnt vmcnt(0) expcnt(0) lgkmcnt(0)
	ds_read_b32 v2, v0
	s_add_i32 s6, 0, 0x23fc4
	v_mov_b32_e32 v0, s6
	ds_read_b32 v0, v0
	s_waitcnt lgkmcnt(1)
	v_cmp_ne_u32_e32 vcc, 0, v2
	s_cbranch_vccnz .LBB0_420
	s_load_dwordx2 s[14:15], s[94:95], 0x4
	s_add_u32 s6, s50, 0x1000
	s_addc_u32 s7, s51, 0
	s_add_u32 s12, s50, 0x1100
	s_addc_u32 s13, s51, 0
	s_waitcnt lgkmcnt(0)
	s_mul_i32 s24, s14, s86
	s_add_u32 s14, s50, 0x1200
	s_mul_i32 s24, s24, s15
	s_addc_u32 s15, s51, 0
	s_add_u32 s16, s50, 0x1300
	s_addc_u32 s17, s51, 0
	s_mov_b32 s25, 1
	v_mov_b32_e32 v16, 0
	s_branch .LBB0_408
